# grid barrier tail hand-written: all workgroups wait on the cross-XCD arrival counter, leader arrival is a fire-and-forget add, generation hops removed
# speedup vs baseline: 1.0045x; 1.0045x over previous
.LBB0_9:
	s_add_u32 s60, s22, 0x100000
	s_addc_u32 s61, s23, 0
	s_add_u32 s3, s22, 0x5200000
	v_writelane_b32 v252, s3, 1
	s_addc_u32 s3, s23, 0
	s_add_u32 s24, s22, 0x5a00000
	v_writelane_b32 v252, s3, 2
	s_addc_u32 s25, s23, 0
	v_writelane_b32 v252, s24, 3
	v_and_b32_e32 v226, 0x3ff, v0
	v_mbcnt_lo_u32_b32 v2, -1, 0
	v_writelane_b32 v252, s25, 4
	s_add_u32 s24, s22, 0x7e00000
	s_addc_u32 s25, s23, 0
	v_writelane_b32 v252, s24, 5
	v_mov_b32_e32 v33, 0
	v_mov_b32_e32 v227, 0x358637bd
	v_writelane_b32 v252, s25, 6
	s_add_u32 s24, s22, 0xe100000
	s_addc_u32 s25, s23, 0
	v_writelane_b32 v252, s24, 7
	s_add_u32 s3, s22, 0x10500000
	v_mov_b32_e32 v228, 0x260
	v_writelane_b32 v252, s25, 8
	v_writelane_b32 v252, s3, 9
	s_addc_u32 s3, s23, 0
	s_add_u32 s35, s22, 0x11700000
	s_addc_u32 s36, s23, 0
	s_add_u32 s37, s22, 0x12900000
	v_writelane_b32 v252, s3, 10
	s_addc_u32 s38, s23, 0
	s_add_u32 s62, s22, 0x200000
	v_readlane_b32 s34, v252, 0
	s_addc_u32 s63, s23, 0
	s_lshl_b32 s64, s34, 3
	s_add_u32 s0, s0, 0xa0
	s_addc_u32 s1, s1, 0
	s_add_u32 s65, s22, 0x13b00000
	v_writelane_b32 v252, s0, 11
	s_addc_u32 s66, s23, 0
	v_mov_b32_e32 v179, 1
	v_writelane_b32 v252, s1, 12
	s_add_u32 s0, s22, 0x4000
	v_writelane_b32 v252, s0, 13
	s_addc_u32 s0, s23, 0
	s_and_b32 s3, s34, 7
	v_writelane_b32 v252, s0, 14
	s_or_b32 s0, s3, 64
	v_writelane_b32 v252, s0, 15
	s_ashr_i32 s0, s34, 3
	v_writelane_b32 v252, s0, 16
	s_ashr_i32 s0, s34, 31
	s_cmpk_gt_i32 s34, 0x8f
	s_cselect_b64 s[24:25], -1, 0
	v_writelane_b32 v252, s24, 17
	s_cmpk_lt_u32 s34, 0xe0
	s_mov_b32 s1, 0
	v_writelane_b32 v252, s25, 18
	s_cselect_b64 s[24:25], -1, 0
	v_writelane_b32 v252, s24, 19
	v_mbcnt_hi_u32_b32 v229, -1, v2
	v_mov_b32_e32 v230, 0x9000
	v_writelane_b32 v252, s25, 20
	s_add_i32 s24, s64, 0xfffffb80
	v_writelane_b32 v252, s24, 21
	v_writelane_b32 v252, s0, 22
	s_lshr_b32 s0, s0, 29
	s_add_i32 s0, s34, s0
	s_ashr_i32 s24, s0, 3
	s_and_b32 s0, s0, -8
	s_sub_i32 s0, s34, s0
	v_writelane_b32 v252, s24, 23
	s_cmp_lt_i32 s0, 0
	v_writelane_b32 v252, s0, 24
	s_cselect_b64 s[24:25], -1, 0
	v_writelane_b32 v252, s24, 25
	s_cmpk_gt_i32 s34, 0xcf
	v_mov_b32_e32 v36, 0x3f803f80
	v_writelane_b32 v252, s25, 26
	s_cselect_b64 s[24:25], -1, 0
	s_lshr_b32 s27, s34, 3
	s_add_i32 s28, s27, -4
	v_writelane_b32 v252, s24, 27
	v_med3_i32 v1, s28, 0, 24
	s_lshl_b32 s0, s3, 7
	v_writelane_b32 v252, s25, 28
	s_lshl_b32 s24, s27, 2
	v_readfirstlane_b32 s29, v1
	s_add_i32 s0, s0, s24
	s_lshl_b32 s24, s3, 6
	s_lshl_b32 s25, s29, 1
	s_or_b32 s30, s25, s24
	s_lshl_b32 s24, s3, 3
	s_or_b32 s39, s24, 0x200
	s_or_b32 s24, s0, 1
	s_mov_b32 s25, s1
	s_lshl_b64 s[24:25], s[24:25], 14
	v_writelane_b32 v252, s24, 29
	s_lshl_b32 s31, s30, 15
	s_mulk_i32 s29, 0x7c
	v_writelane_b32 v252, s25, 30
	s_or_b32 s24, s0, 2
	s_mov_b32 s25, s1
	s_lshl_b64 s[24:25], s[24:25], 14
	v_writelane_b32 v252, s24, 31
	v_and_b32_e32 v1, 63, v0
	v_and_b32_e32 v0, 0x3fffffff, v0
	v_writelane_b32 v252, s25, 32
	s_lshl_b64 s[24:25], s[0:1], 14
	v_writelane_b32 v252, s24, 33
	s_or_b32 s0, s0, 3
	s_lshl_b64 s[40:41], s[0:1], 14
	v_writelane_b32 v252, s25, 34
	s_add_i32 s24, s64, 0x2700
	v_writelane_b32 v252, s24, 35
	s_lshl_b32 s24, s27, 6
	v_writelane_b32 v252, s40, 36
	s_add_u32 s0, s35, s31
	s_mulk_i32 s27, 0x7c
	v_writelane_b32 v252, s41, 37
	v_writelane_b32 v252, s0, 38
	s_addc_u32 s0, s36, 0
	v_writelane_b32 v252, s0, 39
	s_add_u32 s0, s37, s31
	v_writelane_b32 v252, s0, 40
	s_addc_u32 s0, s38, 0
	s_lshl_b32 s25, s3, 11
	v_writelane_b32 v252, s0, 41
	s_add_i32 s0, s25, s24
	s_cmp_lt_u32 s34, 32
	v_writelane_b32 v252, s0, 42
	s_cselect_b64 s[40:41], -1, 0
	v_writelane_b32 v252, s40, 43
	s_lshl_b32 s0, s3, 8
	v_mov_b32_e32 v231, 0x200
	v_writelane_b32 v252, s41, 44
	s_lshl_b32 s40, s3, 18
	s_and_b32 s3, s34, 24
	v_writelane_b32 v252, s3, 45
	s_or_b32 s3, s0, 0x4000
	v_writelane_b32 v252, s3, 46
	v_writelane_b32 v252, s39, 47
	s_lshl_b32 s3, s39, 15
	v_writelane_b32 v252, s35, 48
	s_add_u32 s24, s35, s3
	v_writelane_b32 v252, s24, 49
	v_writelane_b32 v252, s36, 50
	s_addc_u32 s24, s36, 0
	v_writelane_b32 v252, s24, 51
	v_writelane_b32 v252, s37, 52
	s_add_u32 s3, s37, s3
	v_writelane_b32 v252, s3, 53
	v_writelane_b32 v252, s38, 54
	s_addc_u32 s3, s38, 0
	v_writelane_b32 v252, s3, 55
	s_and_b32 s3, s34, -8
	s_cmp_gt_u32 s34, 31
	v_writelane_b32 v252, s3, 56
	s_cselect_b64 s[36:37], -1, 0
	v_writelane_b32 v252, s36, 57
	s_lshl_b32 s3, s28, 3
	v_mov_b32_e32 v232, 0x400
	v_writelane_b32 v252, s37, 58
	v_writelane_b32 v252, s3, 59
	s_or_b32 s3, s0, 0x3801
	v_writelane_b32 v252, s3, 60
	s_or_b32 s3, s0, 0x3802
	v_writelane_b32 v252, s3, 61
	s_or_b32 s3, s0, 0x3803
	v_writelane_b32 v252, s3, 62
	s_or_b32 s3, s0, 0x3804
	v_writelane_b32 v252, s3, 63
	s_or_b32 s3, s0, 0x3805
	v_writelane_b32 v253, s3, 0
	s_or_b32 s3, s0, 0x3806
	v_writelane_b32 v253, s3, 1
	s_or_b32 s0, s0, 0x3807
	v_writelane_b32 v253, s0, 2
	s_add_i32 s0, s25, -1
	v_writelane_b32 v253, s0, 3
	v_writelane_b32 v253, s25, 4
	s_or_b32 s0, s25, 1
	v_writelane_b32 v253, s0, 5
	s_add_i32 s0, s34, 32
	v_writelane_b32 v253, s0, 6
	s_add_u32 s0, s22, 0x151000
	v_writelane_b32 v253, s0, 7
	s_addc_u32 s0, s23, 0
	v_writelane_b32 v253, s0, 8
	s_add_u32 s0, s22, 0x8000
	v_writelane_b32 v253, s0, 9
	s_addc_u32 s0, s23, 0
	v_writelane_b32 v253, s0, 10
	s_add_u32 s0, s22, 0x80000
	v_writelane_b32 v253, s0, 11
	s_addc_u32 s0, s23, 0
	v_writelane_b32 v253, s0, 12
	s_add_i32 s0, s64, 0x4000
	s_add_i32 s67, s64, 0x4008
	s_cmp_gt_i32 s34, 31
	v_writelane_b32 v253, s0, 13
	s_cselect_b64 s[24:25], -1, 0
	v_writelane_b32 v253, s24, 14
	s_add_i32 s0, s64, 0x3100
	s_cmp_lt_i32 s34, 32
	v_writelane_b32 v253, s25, 15
	v_writelane_b32 v253, s0, 16
	s_cselect_b64 s[24:25], -1, 0
	s_lshr_b32 s0, s34, 2
	s_add_i32 s3, s0, 64
	s_max_i32 s0, s34, 0
	v_writelane_b32 v253, s24, 17
	s_and_b32 s0, s0, 3
	s_cmp_gt_i32 s34, -1
	v_writelane_b32 v253, s25, 18
	v_writelane_b32 v253, s0, 19
	s_cselect_b64 s[24:25], -1, 0
	v_writelane_b32 v253, s24, 20
	v_mov_b32_e32 v233, 0x800
	v_mov_b32_e32 v234, 0x1000
	v_writelane_b32 v253, s25, 21
	s_and_b64 s[24:25], s[24:25], exec
	v_writelane_b32 v253, s3, 22
	s_cselect_b32 s0, s3, 0
	v_writelane_b32 v253, s0, 23
	s_and_b32 s0, s34, 3
	s_cmpk_lt_i32 s34, 0x120
	s_cselect_b64 s[68:69], -1, 0
	s_cmp_eq_u32 s26, 2
	s_cselect_b64 s[70:71], -1, 0
	s_add_u32 s24, s22, 0x200
	v_writelane_b32 v253, s0, 24
	s_addc_u32 s25, s23, 0
	v_writelane_b32 v253, s24, 25
	v_mov_b32_e32 v235, 0x2000
	v_mov_b32_e32 v236, 0x4000
	v_writelane_b32 v253, s25, 26
	s_add_u32 s24, s22, 0x1000
	s_addc_u32 s25, s23, 0
	v_writelane_b32 v253, s24, 27
	v_mov_b32_e32 v237, 0x8000
	v_mov_b32_e32 v238, 0x100
	v_writelane_b32 v253, s25, 28
	s_add_u32 s24, s22, 0x1100
	s_addc_u32 s25, s23, 0
	v_writelane_b32 v253, s24, 29
	v_mov_b32_e32 v239, 0x80
	v_mov_b32_e32 v245, 0x1000000
	v_writelane_b32 v253, s25, 30
	s_add_u32 s24, s22, 0x1200
	s_addc_u32 s25, s23, 0
	v_writelane_b32 v253, s24, 31
	v_mov_b32_e32 v250, 0x100000
	v_mov_b32_e32 v251, 0x80000
	v_writelane_b32 v253, s25, 32
	s_add_u32 s24, s22, 0x1300
	s_addc_u32 s25, s23, 0
	v_writelane_b32 v253, s24, 33
	s_cmp_eq_u32 s2, 15
	v_mov_b32_e32 v240, 0x40000
	v_writelane_b32 v253, s25, 34
	s_cselect_b64 s[24:25], -1, 0
	v_writelane_b32 v253, s24, 35
	s_cmp_eq_u32 s2, 14
	v_mov_b32_e32 v241, 0x20000
	v_writelane_b32 v253, s25, 36
	s_cselect_b64 s[24:25], -1, 0
	v_writelane_b32 v253, s24, 37
	s_cmp_eq_u32 s2, 13
	v_mov_b32_e32 v242, 0xff800000
	v_writelane_b32 v253, s25, 38
	s_cselect_b64 s[24:25], -1, 0
	v_writelane_b32 v253, s24, 39
	s_cmp_eq_u32 s2, 12
	v_mov_b32_e32 v243, 0x7ff
	v_writelane_b32 v253, s25, 40
	s_cselect_b64 s[24:25], -1, 0
	v_writelane_b32 v253, s24, 41
	s_cmp_eq_u32 s2, 11
	v_mov_b64_e32 v[180:181], 0x1e8481
	v_writelane_b32 v253, s25, 42
	s_cselect_b64 s[24:25], -1, 0
	v_writelane_b32 v253, s24, 43
	s_cmp_eq_u32 s2, 10
	s_movk_i32 s72, 0x4000
	v_writelane_b32 v253, s25, 44
	s_cselect_b64 s[24:25], -1, 0
	v_writelane_b32 v253, s24, 45
	s_cmp_eq_u32 s2, 9
	s_movk_i32 s96, 0x84
	v_writelane_b32 v253, s25, 46
	s_cselect_b64 s[24:25], -1, 0
	v_writelane_b32 v253, s24, 47
	s_cmp_eq_u32 s2, 8
	s_movk_i32 s73, 0x2000
	v_writelane_b32 v253, s25, 48
	s_cselect_b64 s[24:25], -1, 0
	v_writelane_b32 v253, s24, 49
	s_cmp_eq_u32 s2, 7
	s_mov_b32 s74, 0x8000
	v_writelane_b32 v253, s25, 50
	s_cselect_b64 s[24:25], -1, 0
	v_writelane_b32 v253, s24, 51
	s_cmp_eq_u32 s2, 6
	s_mov_b32 s75, 0x10000
	v_writelane_b32 v253, s25, 52
	s_cselect_b64 s[24:25], -1, 0
	v_writelane_b32 v253, s24, 53
	s_cmp_eq_u32 s2, 5
	s_mov_b32 s76, 0x18000
	v_writelane_b32 v253, s25, 54
	s_cselect_b64 s[24:25], -1, 0
	v_writelane_b32 v253, s24, 55
	s_cmp_eq_u32 s2, 4
	s_mov_b32 s77, 0x2c000
	v_writelane_b32 v253, s25, 56
	s_cselect_b64 s[24:25], -1, 0
	v_writelane_b32 v253, s24, 57
	s_cmp_eq_u32 s2, 3
	v_cmp_gt_u32_e64 s[36:37], 64, v226
	v_writelane_b32 v253, s25, 58
	s_cselect_b64 s[24:25], -1, 0
	v_writelane_b32 v253, s24, 59
	s_cmp_eq_u32 s2, 2
	s_nop 0
	v_writelane_b32 v253, s25, 60
	s_cselect_b64 s[24:25], -1, 0
	v_writelane_b32 v253, s24, 61
	s_cmp_eq_u32 s2, 1
	s_nop 0
	v_writelane_b32 v253, s25, 62
	s_cselect_b64 s[24:25], -1, 0
	v_writelane_b32 v253, s24, 63
	s_cmp_eq_u32 s2, 0
	s_nop 0
	v_writelane_b32 v254, s25, 0
	s_cselect_b64 s[24:25], -1, 0
	s_lshl_b32 s0, s2, 8
	s_add_u32 s0, s22, s0
	v_writelane_b32 v254, s24, 1
	s_addc_u32 s2, s23, 0
	s_nop 0
	v_writelane_b32 v254, s25, 2
	s_add_u32 s24, s0, 0x1400
	s_addc_u32 s25, s2, 0
	v_writelane_b32 v254, s24, 3
	s_nop 1
	v_writelane_b32 v254, s25, 4
	s_add_u32 s24, s0, 0x2400
	s_addc_u32 s25, s2, 0
	v_writelane_b32 v254, s24, 5
	s_add_u32 s2, s22, 0x3400
	s_addc_u32 s3, s23, 0
	v_writelane_b32 v254, s25, 6
	v_writelane_b32 v254, s2, 7
	s_nop 1
	v_writelane_b32 v254, s3, 8
	s_add_u32 s2, s22, 0x3500
	s_addc_u32 s3, s23, 0
	v_writelane_b32 v254, s2, 9
	s_add_u32 s0, s22, 0x13908800
	s_nop 0
	v_writelane_b32 v254, s3, 10
	v_writelane_b32 v254, s0, 11
	s_addc_u32 s0, s23, 0
	v_writelane_b32 v254, s0, 12
	s_sub_i32 s0, s29, s27
	s_add_i32 s2, s30, 2
	s_add_i32 s0, s0, 0
	v_writelane_b32 v254, s2, 13
	s_addk_i32 s0, 0x420
	v_writelane_b32 v254, s0, 14
	s_add_i32 s0, s64, 0xfffff800
	v_writelane_b32 v254, s0, 15
	s_add_u32 s0, s22, s31
	s_addc_u32 s2, s23, 0
	v_writelane_b32 v254, s0, 16
	s_add_u32 s0, s0, 0x12908800
	v_writelane_b32 v254, s0, 17
	v_writelane_b32 v254, s2, 18
	s_addc_u32 s0, s2, 0
	v_writelane_b32 v254, s0, 19
	s_add_u32 s0, s22, s40
	v_writelane_b32 v254, s40, 20
	s_addc_u32 s2, s23, 0
	v_writelane_b32 v254, s0, 21
	s_add_u32 s0, s0, 0x13908800
	v_writelane_b32 v254, s0, 22
	v_writelane_b32 v254, s2, 23
	s_addc_u32 s0, s2, 0
	v_writelane_b32 v254, s0, 24
	s_waitcnt lgkmcnt(0)
	s_add_u32 s0, s88, 0x87000
	v_writelane_b32 v254, s0, 25
	s_addc_u32 s0, s89, 0
	v_writelane_b32 v254, s0, 26
	s_lshl_b32 s0, s34, 9
	v_writelane_b32 v254, s0, 27
	s_add_i32 s0, 0, 0x20100
	v_writelane_b32 v254, s0, 28
	s_add_i32 s0, 0, 0x20110
	v_writelane_b32 v254, s0, 29
	s_add_i32 s0, 0, 0x20120
	v_writelane_b32 v254, s0, 30
	s_add_i32 s0, 0, 0x20130
	v_writelane_b32 v254, s0, 31
	s_add_i32 s0, 0, 0x20140
	v_writelane_b32 v254, s0, 32
	s_add_i32 s0, 0, 0x20150
	v_writelane_b32 v254, s0, 33
	v_cmp_eq_u32_e64 s[2:3], 0, v1
	s_mov_b32 s29, 0xff800000
	s_mov_b64 s[88:89], 0x80
	v_writelane_b32 v254, s2, 34
	s_nop 1
	v_writelane_b32 v254, s3, 35
	s_mov_b32 s3, 2
	v_writelane_b32 v254, s2, 36
	s_nop 1
	v_writelane_b32 v254, s3, 37
	v_cmp_eq_u32_e64 s[2:3], 0, v0
	s_nop 1
	v_writelane_b32 v254, s2, 38
	s_nop 1
	v_writelane_b32 v254, s3, 39
	v_cmp_eq_u32_e64 s[2:3], 0, v226
	s_nop 1
	v_writelane_b32 v254, s2, 40
	s_nop 1
	v_writelane_b32 v254, s3, 41
	v_writelane_b32 v254, s56, 42
	s_nop 1
	v_writelane_b32 v254, s57, 43
	v_writelane_b32 v254, s58, 44
	v_writelane_b32 v254, s59, 45
	v_writelane_b32 v254, s60, 46
	s_nop 1
	v_writelane_b32 v254, s61, 47
	v_writelane_b32 v254, s62, 48
	v_writelane_b32 v254, s63, 49
	v_writelane_b32 v254, s64, 50
	v_writelane_b32 v254, s65, 51
	v_writelane_b32 v254, s66, 52
	v_writelane_b32 v254, s67, 53
	v_writelane_b32 v254, s68, 54
	s_nop 1
	v_writelane_b32 v254, s69, 55
	v_writelane_b32 v254, s70, 56
	s_nop 1
	v_writelane_b32 v254, s71, 57
	s_branch .LBB0_13
.LBB0_11:
	s_or_b64 exec, exec, s[24:25]
	s_waitcnt lgkmcnt(0)
	s_barrier

.LBB0_1206:
	v_readlane_b32 s2, v254, 3
	v_readlane_b32 s3, v254, 4
	v_cvt_f32_u32_e32 v1, v2
	v_sub_u32_e32 v4, 0, v2
	v_rcp_iflag_f32_e32 v1, v1
	s_nop 1
	global_atomic_add v3, v33, v179, s[2:3] sc0
	v_mul_f32_e32 v1, 0x4f7ffffe, v1
	v_cvt_u32_f32_e32 v1, v1
	v_mul_lo_u32 v4, v4, v1
	v_mul_hi_u32 v4, v1, v4
	v_add_u32_e32 v1, v1, v4
	s_waitcnt vmcnt(0)
	v_mul_hi_u32 v1, v3, v1
	v_mul_lo_u32 v4, v1, v2
	v_sub_u32_e32 v4, v3, v4
	v_add_u32_e32 v5, 1, v1
	v_cmp_ge_u32_e32 vcc, v4, v2
	v_add_u32_e32 v3, 1, v3
	s_nop 0
	v_cndmask_b32_e32 v1, v1, v5, vcc
	v_sub_u32_e32 v5, v4, v2
	v_cndmask_b32_e32 v4, v4, v5, vcc
	v_add_u32_e32 v5, 1, v1
	v_cmp_ge_u32_e32 vcc, v4, v2
	s_nop 1
	v_cndmask_b32_e32 v1, v1, v5, vcc
	v_mul_lo_u32 v4, v2, v1
	v_add_u32_e32 v2, v4, v2
	v_cmp_ne_u32_e32 vcc, v3, v2
	s_waitcnt lgkmcnt(0)
	v_add_u32_e32 v6, 1, v1
	v_mul_lo_u32 v6, v6, v0
	v_readlane_b32 s2, v254, 7
	v_readlane_b32 s3, v254, 8
	s_mov_b32 s0, 0
	s_cbranch_vccnz .Lmy_bar_poll
	buffer_wbl2 sc1
	s_waitcnt vmcnt(0)
	global_atomic_add v33, v179, s[2:3]
.Lmy_bar_poll:
	s_nop 4
	buffer_inv sc1
.Lmy_bar_loop:
	global_load_dword v0, v33, s[2:3] sc1
	s_waitcnt vmcnt(0)
	v_cmp_lt_u32_e32 vcc, v0, v6
	s_cbranch_vccz .Lmy_bar_done
	s_sleep 1
	s_add_i32 s0, s0, 1
	s_and_b32 s30, s0, 0xff
	s_cmp_lg_u32 s30, 0
	s_cbranch_scc1 .Lmy_bar_loop
	v_readlane_b32 s30, v253, 25
	v_readlane_b32 s31, v253, 26
	s_nop 4
	global_load_dword v0, v33, s[30:31] sc1
	s_waitcnt vmcnt(0)
	v_cmp_ne_u32_e32 vcc, 0, v0
	s_cbranch_vccnz .Lmy_bar_done
	s_cmp_lt_u32 s0, 0x40001
	s_cbranch_scc1 .Lmy_bar_loop
	global_atomic_add v33, v179, s[30:31]
.Lmy_bar_done:
	s_waitcnt vmcnt(0)
	s_getpc_b64 s[98:99]
